# v21 + SwiGLU epilogue element math re-emitted as 8 interleaved chains (no nops/movs/packed ops)
# baseline (speedup 1.0000x reference)
; __device__ __forceinline__ unsigned cvt_pk_bf16(float lo, float hi) { unsigned r; asm volatile("v_cvt_pk_bf16_f32 %0, %1, %2" : "=v"(r) : "v"(lo), "v"(hi)); return r; }
;     __device__ __forceinline__ void operator()(const f32x4 (&acc)[2][2][4][2], const Unit& u, int wr, int wc, int fr, int fq) const {
;     ...
; #pragma unroll
;         for (int ai = 0; ai < 2; ++ai)
; #pragma unroll
;             for (int m = 0; m < 4; ++m) {
;                 const int row = row0 + ai * HALF + m * 16;
;                 const float rs = rsa[ai][m];
;                 float h[8];
; #pragma unroll
;                 for (int n = 0; n < 2; ++n)
; #pragma unroll
;                     for (int e = 0; e < 4; ++e) {
;                         const float g = acc[ai][0][m][n][e] * rs, uu = acc[ai][1][m][n][e] * rs;
;                         const float sg = __builtin_amdgcn_rcpf(1.f + __builtin_amdgcn_exp2f(g * -1.4426950408889634f));
;                         h[n * 4 + e] = g * sg * uu;
;                     }
;                 u32x4 w; w.x = cvt_pk_bf16(h[0], h[1]); w.y = cvt_pk_bf16(h[2], h[3]); w.z = cvt_pk_bf16(h[4], h[5]); w.w = cvt_pk_bf16(h[6], h[7]);
;                 *(u32x4*)(H + (size_t)row * ldc + u.pn * HALF + wc * 32 + 8 * fq) = w;
.LBB0_317:
	s_lshl_b32 s52, s78, 7
	s_ashr_i32 s53, s52, 31
	s_lshl_b64 s[52:53], s[52:53], 1
	s_and_b64 vcc, exec, s[36:37]
	v_mul_f32_e32 v188, v122, v186
	v_mul_f32_e32 v204, v126, v186
	v_mul_f32_e32 v189, v123, v186
	v_mul_f32_e32 v205, v127, v186
	v_mul_f32_e32 v190, v124, v186
	v_mul_f32_e32 v206, v128, v186
	v_mul_f32_e32 v191, v125, v186
	v_mul_f32_e32 v207, v129, v186
	v_mul_f32_e32 v192, v114, v186
	v_mul_f32_e32 v208, v118, v186
	v_mul_f32_e32 v193, v115, v186
	v_mul_f32_e32 v209, v119, v186
	v_mul_f32_e32 v194, v116, v186
	v_mul_f32_e32 v210, v120, v186
	v_mul_f32_e32 v195, v117, v186
	v_mul_f32_e32 v211, v121, v186
	v_mul_f32_e32 v212, 0xbfb8aa3b, v188
	v_mul_f32_e32 v213, 0xbfb8aa3b, v189
	v_mul_f32_e32 v214, 0xbfb8aa3b, v190
	v_mul_f32_e32 v215, 0xbfb8aa3b, v191
	v_mul_f32_e32 v216, 0xbfb8aa3b, v192
	v_mul_f32_e32 v217, 0xbfb8aa3b, v193
	v_mul_f32_e32 v218, 0xbfb8aa3b, v194
	v_mul_f32_e32 v219, 0xbfb8aa3b, v195
	v_exp_f32_e32 v212, v212
	v_exp_f32_e32 v213, v213
	v_exp_f32_e32 v214, v214
	v_exp_f32_e32 v215, v215
	v_exp_f32_e32 v216, v216
	v_exp_f32_e32 v217, v217
	v_exp_f32_e32 v218, v218
	v_exp_f32_e32 v219, v219
	v_add_f32_e32 v212, 1.0, v212
	v_add_f32_e32 v213, 1.0, v213
	v_add_f32_e32 v214, 1.0, v214
	v_add_f32_e32 v215, 1.0, v215
	v_add_f32_e32 v216, 1.0, v216
	v_add_f32_e32 v217, 1.0, v217
	v_add_f32_e32 v218, 1.0, v218
	v_add_f32_e32 v219, 1.0, v219
	v_rcp_f32_e32 v212, v212
	v_rcp_f32_e32 v213, v213
	v_rcp_f32_e32 v214, v214
	v_rcp_f32_e32 v215, v215
	v_rcp_f32_e32 v216, v216
	v_rcp_f32_e32 v217, v217
	v_rcp_f32_e32 v218, v218
	v_rcp_f32_e32 v219, v219
	v_mul_f32_e32 v212, v188, v212
	v_mul_f32_e32 v213, v189, v213
	v_mul_f32_e32 v214, v190, v214
	v_mul_f32_e32 v215, v191, v215
	v_mul_f32_e32 v216, v192, v216
	v_mul_f32_e32 v217, v193, v217
	v_mul_f32_e32 v218, v194, v218
	v_mul_f32_e32 v219, v195, v219
	v_mul_f32_e32 v126, v204, v212
	v_mul_f32_e32 v127, v205, v213
	v_mul_f32_e32 v128, v206, v214
	v_mul_f32_e32 v124, v207, v215
	v_mul_f32_e32 v118, v208, v216
	v_mul_f32_e32 v119, v209, v217
	v_mul_f32_e32 v120, v210, v218
	v_mul_f32_e32 v114, v211, v219
	v_cvt_pk_bf16_f32 v116, v126, v127
	v_cvt_pk_bf16_f32 v117, v128, v124
	v_cvt_pk_bf16_f32 v118, v118, v119
	v_cvt_pk_bf16_f32 v119, v120, v114
	v_mov_b64_e32 v[114:115], s[76:77]
	v_mad_u64_u32 v[120:121], s[54:55], v184, s63, v[114:115]
	v_mov_b32_e32 v122, v121
	v_mad_u64_u32 v[122:123], s[54:55], v185, s63, v[122:123]
	v_mov_b32_e32 v121, v122
	v_lshl_add_u64 v[120:121], v[120:121], 0, s[52:53]
	v_lshl_add_u64 v[120:121], v[120:121], 0, s[24:25]
	v_lshl_add_u64 v[120:121], v[120:121], 0, v[174:175]
	global_store_dwordx4 v[120:121], v[116:119], off
	s_nop 1
	v_mul_f32_e32 v188, v106, v182
	v_mul_f32_e32 v204, v110, v182
	v_mul_f32_e32 v189, v107, v182
	v_mul_f32_e32 v205, v111, v182
	v_mul_f32_e32 v190, v108, v182
	v_mul_f32_e32 v206, v112, v182
	v_mul_f32_e32 v191, v109, v182
	v_mul_f32_e32 v207, v113, v182
	v_mul_f32_e32 v192, v98, v182
	v_mul_f32_e32 v208, v102, v182
	v_mul_f32_e32 v193, v99, v182
	v_mul_f32_e32 v209, v103, v182
	v_mul_f32_e32 v194, v100, v182
	v_mul_f32_e32 v210, v104, v182
	v_mul_f32_e32 v195, v101, v182
	v_mul_f32_e32 v211, v105, v182
	v_mul_f32_e32 v212, 0xbfb8aa3b, v188
	v_mul_f32_e32 v213, 0xbfb8aa3b, v189
	v_mul_f32_e32 v214, 0xbfb8aa3b, v190
	v_mul_f32_e32 v215, 0xbfb8aa3b, v191
	v_mul_f32_e32 v216, 0xbfb8aa3b, v192
	v_mul_f32_e32 v217, 0xbfb8aa3b, v193
	v_mul_f32_e32 v218, 0xbfb8aa3b, v194
	v_mul_f32_e32 v219, 0xbfb8aa3b, v195
	v_exp_f32_e32 v212, v212
	v_exp_f32_e32 v213, v213
	v_exp_f32_e32 v214, v214
	v_exp_f32_e32 v215, v215
	v_exp_f32_e32 v216, v216
	v_exp_f32_e32 v217, v217
	v_exp_f32_e32 v218, v218
	v_exp_f32_e32 v219, v219
	v_add_f32_e32 v212, 1.0, v212
	v_add_f32_e32 v213, 1.0, v213
	v_add_f32_e32 v214, 1.0, v214
	v_add_f32_e32 v215, 1.0, v215
	v_add_f32_e32 v216, 1.0, v216
	v_add_f32_e32 v217, 1.0, v217
	v_add_f32_e32 v218, 1.0, v218
	v_add_f32_e32 v219, 1.0, v219
	v_rcp_f32_e32 v212, v212
	v_rcp_f32_e32 v213, v213
	v_rcp_f32_e32 v214, v214
	v_rcp_f32_e32 v215, v215
	v_rcp_f32_e32 v216, v216
	v_rcp_f32_e32 v217, v217
	v_rcp_f32_e32 v218, v218
	v_rcp_f32_e32 v219, v219
	v_mul_f32_e32 v212, v188, v212
	v_mul_f32_e32 v213, v189, v213
	v_mul_f32_e32 v214, v190, v214
	v_mul_f32_e32 v215, v191, v215
	v_mul_f32_e32 v216, v192, v216
	v_mul_f32_e32 v217, v193, v217
	v_mul_f32_e32 v218, v194, v218
	v_mul_f32_e32 v219, v195, v219
	v_mul_f32_e32 v110, v204, v212
	v_mul_f32_e32 v111, v205, v213
	v_mul_f32_e32 v112, v206, v214
	v_mul_f32_e32 v108, v207, v215
	v_mul_f32_e32 v102, v208, v216
	v_mul_f32_e32 v103, v209, v217
	v_mul_f32_e32 v104, v210, v218
	v_mul_f32_e32 v101, v211, v219
	v_cvt_pk_bf16_f32 v98, v110, v111
	v_cvt_pk_bf16_f32 v99, v112, v108
	v_cvt_pk_bf16_f32 v100, v102, v103
	v_mad_u64_u32 v[102:103], s[54:55], v172, s63, v[114:115]
	v_cvt_pk_bf16_f32 v101, v104, v101
	v_mov_b32_e32 v104, v103
	v_mad_u64_u32 v[104:105], s[54:55], v173, s63, v[104:105]
	v_mov_b32_e32 v103, v104
	v_lshl_add_u64 v[102:103], v[102:103], 0, s[52:53]
	v_lshl_add_u64 v[102:103], v[102:103], 0, s[24:25]
	v_lshl_add_u64 v[102:103], v[102:103], 0, v[174:175]
	global_store_dwordx4 v[102:103], v[98:101], off
	s_nop 1
	v_mul_f32_e32 v188, v90, v176
	v_mul_f32_e32 v204, v94, v176
	v_mul_f32_e32 v189, v91, v176
	v_mul_f32_e32 v205, v95, v176
	v_mul_f32_e32 v190, v92, v176
	v_mul_f32_e32 v206, v96, v176
	v_mul_f32_e32 v191, v93, v176
	v_mul_f32_e32 v207, v97, v176
	v_mul_f32_e32 v192, v82, v176
	v_mul_f32_e32 v208, v86, v176
	v_mul_f32_e32 v193, v83, v176
	v_mul_f32_e32 v209, v87, v176
	v_mul_f32_e32 v194, v84, v176
	v_mul_f32_e32 v210, v88, v176
; __device__ __forceinline__ unsigned cvt_pk_bf16(float lo, float hi) { unsigned r; asm volatile("v_cvt_pk_bf16_f32 %0, %1, %2" : "=v"(r) : "v"(lo), "v"(hi)); return r; }
;     __device__ __forceinline__ void operator()(const f32x4 (&acc)[2][2][4][2], const Unit& u, int wr, int wc, int fr, int fq) const {
;     ...
; #pragma unroll
;         for (int ai = 0; ai < 2; ++ai)
; #pragma unroll
;             for (int m = 0; m < 4; ++m) {
;                 const int row = row0 + ai * HALF + m * 16;
;                 const float rs = rsa[ai][m];
;                 float h[8];
; #pragma unroll
;                 for (int n = 0; n < 2; ++n)
; #pragma unroll
;                     for (int e = 0; e < 4; ++e) {
;                         const float g = acc[ai][0][m][n][e] * rs, uu = acc[ai][1][m][n][e] * rs;
;                         const float sg = __builtin_amdgcn_rcpf(1.f + __builtin_amdgcn_exp2f(g * -1.4426950408889634f));
;                         h[n * 4 + e] = g * sg * uu;
;                     }
;                 u32x4 w; w.x = cvt_pk_bf16(h[0], h[1]); w.y = cvt_pk_bf16(h[2], h[3]); w.z = cvt_pk_bf16(h[4], h[5]); w.w = cvt_pk_bf16(h[6], h[7]);
;                 *(u32x4*)(H + (size_t)row * ldc + u.pn * HALF + wc * 32 + 8 * fq) = w;
	v_mul_f32_e32 v195, v85, v176
	v_mul_f32_e32 v211, v89, v176
	v_mul_f32_e32 v212, 0xbfb8aa3b, v188
	v_mul_f32_e32 v213, 0xbfb8aa3b, v189
	v_mul_f32_e32 v214, 0xbfb8aa3b, v190
	v_mul_f32_e32 v215, 0xbfb8aa3b, v191
	v_mul_f32_e32 v216, 0xbfb8aa3b, v192
	v_mul_f32_e32 v217, 0xbfb8aa3b, v193
	v_mul_f32_e32 v218, 0xbfb8aa3b, v194
	v_mul_f32_e32 v219, 0xbfb8aa3b, v195
	v_exp_f32_e32 v212, v212
	v_exp_f32_e32 v213, v213
	v_exp_f32_e32 v214, v214
	v_exp_f32_e32 v215, v215
	v_exp_f32_e32 v216, v216
	v_exp_f32_e32 v217, v217
	v_exp_f32_e32 v218, v218
	v_exp_f32_e32 v219, v219
	v_add_f32_e32 v212, 1.0, v212
	v_add_f32_e32 v213, 1.0, v213
	v_add_f32_e32 v214, 1.0, v214
	v_add_f32_e32 v215, 1.0, v215
	v_add_f32_e32 v216, 1.0, v216
	v_add_f32_e32 v217, 1.0, v217
	v_add_f32_e32 v218, 1.0, v218
	v_add_f32_e32 v219, 1.0, v219
	v_rcp_f32_e32 v212, v212
	v_rcp_f32_e32 v213, v213
	v_rcp_f32_e32 v214, v214
	v_rcp_f32_e32 v215, v215
	v_rcp_f32_e32 v216, v216
	v_rcp_f32_e32 v217, v217
	v_rcp_f32_e32 v218, v218
	v_rcp_f32_e32 v219, v219
	v_mul_f32_e32 v212, v188, v212
	v_mul_f32_e32 v213, v189, v213
	v_mul_f32_e32 v214, v190, v214
	v_mul_f32_e32 v215, v191, v215
	v_mul_f32_e32 v216, v192, v216
	v_mul_f32_e32 v217, v193, v217
	v_mul_f32_e32 v218, v194, v218
	v_mul_f32_e32 v219, v195, v219
	v_mul_f32_e32 v94, v204, v212
	v_mul_f32_e32 v95, v205, v213
	v_mul_f32_e32 v96, v206, v214
	v_mul_f32_e32 v92, v207, v215
	v_mul_f32_e32 v86, v208, v216
	v_mul_f32_e32 v87, v209, v217
	v_mul_f32_e32 v88, v210, v218
	v_mul_f32_e32 v85, v211, v219
	v_cvt_pk_bf16_f32 v82, v94, v95
	v_cvt_pk_bf16_f32 v83, v96, v92
	v_cvt_pk_bf16_f32 v84, v86, v87
	v_mad_u64_u32 v[86:87], s[54:55], v168, s63, v[114:115]
	v_cvt_pk_bf16_f32 v85, v88, v85
	v_mov_b32_e32 v88, v87
	v_mad_u64_u32 v[88:89], s[54:55], v169, s63, v[88:89]
	v_mov_b32_e32 v87, v88
	v_lshl_add_u64 v[86:87], v[86:87], 0, s[52:53]
	v_lshl_add_u64 v[86:87], v[86:87], 0, s[24:25]
	v_lshl_add_u64 v[86:87], v[86:87], 0, v[174:175]
	global_store_dwordx4 v[86:87], v[82:85], off
	s_nop 1
	v_mul_f32_e32 v188, v74, v170
	v_mul_f32_e32 v204, v78, v170
	v_mul_f32_e32 v189, v75, v170
	v_mul_f32_e32 v205, v79, v170
	v_mul_f32_e32 v190, v76, v170
	v_mul_f32_e32 v206, v80, v170
	v_mul_f32_e32 v191, v77, v170
	v_mul_f32_e32 v207, v81, v170
	v_mul_f32_e32 v192, v66, v170
	v_mul_f32_e32 v208, v70, v170
	v_mul_f32_e32 v193, v67, v170
	v_mul_f32_e32 v209, v71, v170
	v_mul_f32_e32 v194, v68, v170
	v_mul_f32_e32 v210, v72, v170
	v_mul_f32_e32 v195, v69, v170
	v_mul_f32_e32 v211, v73, v170
	v_mul_f32_e32 v212, 0xbfb8aa3b, v188
	v_mul_f32_e32 v213, 0xbfb8aa3b, v189
	v_mul_f32_e32 v214, 0xbfb8aa3b, v190
	v_mul_f32_e32 v215, 0xbfb8aa3b, v191
	v_mul_f32_e32 v216, 0xbfb8aa3b, v192
	v_mul_f32_e32 v217, 0xbfb8aa3b, v193
	v_mul_f32_e32 v218, 0xbfb8aa3b, v194
	v_mul_f32_e32 v219, 0xbfb8aa3b, v195
	v_exp_f32_e32 v212, v212
	v_exp_f32_e32 v213, v213
	v_exp_f32_e32 v214, v214
	v_exp_f32_e32 v215, v215
	v_exp_f32_e32 v216, v216
	v_exp_f32_e32 v217, v217
	v_exp_f32_e32 v218, v218
	v_exp_f32_e32 v219, v219
	v_add_f32_e32 v212, 1.0, v212
	v_add_f32_e32 v213, 1.0, v213
	v_add_f32_e32 v214, 1.0, v214
	v_add_f32_e32 v215, 1.0, v215
	v_add_f32_e32 v216, 1.0, v216
	v_add_f32_e32 v217, 1.0, v217
	v_add_f32_e32 v218, 1.0, v218
	v_add_f32_e32 v219, 1.0, v219
	v_rcp_f32_e32 v212, v212
	v_rcp_f32_e32 v213, v213
	v_rcp_f32_e32 v214, v214
	v_rcp_f32_e32 v215, v215
	v_rcp_f32_e32 v216, v216
	v_rcp_f32_e32 v217, v217
	v_rcp_f32_e32 v218, v218
	v_rcp_f32_e32 v219, v219
	v_mul_f32_e32 v212, v188, v212
	v_mul_f32_e32 v213, v189, v213
	v_mul_f32_e32 v214, v190, v214
	v_mul_f32_e32 v215, v191, v215
	v_mul_f32_e32 v216, v192, v216
	v_mul_f32_e32 v217, v193, v217
	v_mul_f32_e32 v218, v194, v218
	v_mul_f32_e32 v219, v195, v219
	v_mul_f32_e32 v78, v204, v212
	v_mul_f32_e32 v79, v205, v213
	v_mul_f32_e32 v80, v206, v214
	v_mul_f32_e32 v76, v207, v215
	v_mul_f32_e32 v70, v208, v216
	v_mul_f32_e32 v71, v209, v217
	v_mul_f32_e32 v72, v210, v218
	v_mul_f32_e32 v69, v211, v219
	v_cvt_pk_bf16_f32 v66, v78, v79
	v_cvt_pk_bf16_f32 v67, v80, v76
	v_cvt_pk_bf16_f32 v68, v70, v71
	v_mad_u64_u32 v[70:71], s[54:55], v162, s63, v[114:115]
	v_cvt_pk_bf16_f32 v69, v72, v69
	v_mov_b32_e32 v72, v71
	v_mad_u64_u32 v[72:73], s[54:55], v163, s63, v[72:73]
	v_mov_b32_e32 v71, v72
	v_lshl_add_u64 v[70:71], v[70:71], 0, s[52:53]
	v_lshl_add_u64 v[70:71], v[70:71], 0, s[24:25]
	v_lshl_add_u64 v[70:71], v[70:71], 0, v[174:175]
	global_store_dwordx4 v[70:71], v[66:69], off
	s_nop 1
	v_mul_f32_e32 v188, v58, v166
	v_mul_f32_e32 v204, v62, v166
	v_mul_f32_e32 v189, v59, v166
	v_mul_f32_e32 v205, v63, v166
	v_mul_f32_e32 v190, v60, v166
	v_mul_f32_e32 v206, v64, v166
	v_mul_f32_e32 v191, v61, v166
	v_mul_f32_e32 v207, v65, v166
	v_mul_f32_e32 v192, v50, v166
	v_mul_f32_e32 v208, v54, v166
	v_mul_f32_e32 v193, v51, v166
	v_mul_f32_e32 v209, v55, v166
	v_mul_f32_e32 v194, v52, v166
	v_mul_f32_e32 v210, v56, v166
	v_mul_f32_e32 v195, v53, v166
	v_mul_f32_e32 v211, v57, v166
	v_mul_f32_e32 v212, 0xbfb8aa3b, v188
	v_mul_f32_e32 v213, 0xbfb8aa3b, v189
	v_mul_f32_e32 v214, 0xbfb8aa3b, v190
	v_mul_f32_e32 v215, 0xbfb8aa3b, v191
	v_mul_f32_e32 v216, 0xbfb8aa3b, v192
	v_mul_f32_e32 v217, 0xbfb8aa3b, v193
	v_mul_f32_e32 v218, 0xbfb8aa3b, v194
	v_mul_f32_e32 v219, 0xbfb8aa3b, v195
	v_exp_f32_e32 v212, v212
	v_exp_f32_e32 v213, v213
	v_exp_f32_e32 v214, v214
	v_exp_f32_e32 v215, v215
	v_exp_f32_e32 v216, v216
	v_exp_f32_e32 v217, v217
	v_exp_f32_e32 v218, v218
	v_exp_f32_e32 v219, v219
	v_add_f32_e32 v212, 1.0, v212
	v_add_f32_e32 v213, 1.0, v213
	v_add_f32_e32 v214, 1.0, v214
	v_add_f32_e32 v215, 1.0, v215
	v_add_f32_e32 v216, 1.0, v216
; __device__ __forceinline__ unsigned cvt_pk_bf16(float lo, float hi) { unsigned r; asm volatile("v_cvt_pk_bf16_f32 %0, %1, %2" : "=v"(r) : "v"(lo), "v"(hi)); return r; }
;     __device__ __forceinline__ void operator()(const f32x4 (&acc)[2][2][4][2], const Unit& u, int wr, int wc, int fr, int fq) const {
;     ...
; #pragma unroll
;         for (int ai = 0; ai < 2; ++ai)
; #pragma unroll
;             for (int m = 0; m < 4; ++m) {
;                 const int row = row0 + ai * HALF + m * 16;
;                 const float rs = rsa[ai][m];
;                 float h[8];
; #pragma unroll
;                 for (int n = 0; n < 2; ++n)
; #pragma unroll
;                     for (int e = 0; e < 4; ++e) {
;                         const float g = acc[ai][0][m][n][e] * rs, uu = acc[ai][1][m][n][e] * rs;
;                         const float sg = __builtin_amdgcn_rcpf(1.f + __builtin_amdgcn_exp2f(g * -1.4426950408889634f));
;                         h[n * 4 + e] = g * sg * uu;
;                     }
;                 u32x4 w; w.x = cvt_pk_bf16(h[0], h[1]); w.y = cvt_pk_bf16(h[2], h[3]); w.z = cvt_pk_bf16(h[4], h[5]); w.w = cvt_pk_bf16(h[6], h[7]);
;                 *(u32x4*)(H + (size_t)row * ldc + u.pn * HALF + wc * 32 + 8 * fq) = w;
	v_add_f32_e32 v217, 1.0, v217
	v_add_f32_e32 v218, 1.0, v218
	v_add_f32_e32 v219, 1.0, v219
	v_rcp_f32_e32 v212, v212
	v_rcp_f32_e32 v213, v213
	v_rcp_f32_e32 v214, v214
	v_rcp_f32_e32 v215, v215
	v_rcp_f32_e32 v216, v216
	v_rcp_f32_e32 v217, v217
	v_rcp_f32_e32 v218, v218
	v_rcp_f32_e32 v219, v219
	v_mul_f32_e32 v212, v188, v212
	v_mul_f32_e32 v213, v189, v213
	v_mul_f32_e32 v214, v190, v214
	v_mul_f32_e32 v215, v191, v215
	v_mul_f32_e32 v216, v192, v216
	v_mul_f32_e32 v217, v193, v217
	v_mul_f32_e32 v218, v194, v218
	v_mul_f32_e32 v219, v195, v219
	v_mul_f32_e32 v62, v204, v212
	v_mul_f32_e32 v63, v205, v213
	v_mul_f32_e32 v64, v206, v214
	v_mul_f32_e32 v60, v207, v215
	v_mul_f32_e32 v54, v208, v216
	v_mul_f32_e32 v55, v209, v217
	v_mul_f32_e32 v56, v210, v218
	v_mul_f32_e32 v53, v211, v219
	v_cvt_pk_bf16_f32 v50, v62, v63
	v_cvt_pk_bf16_f32 v51, v64, v60
	v_cvt_pk_bf16_f32 v52, v54, v55
	v_mad_u64_u32 v[54:55], s[54:55], v158, s63, v[114:115]
	v_cvt_pk_bf16_f32 v53, v56, v53
	v_mov_b32_e32 v56, v55
	v_mad_u64_u32 v[56:57], s[54:55], v159, s63, v[56:57]
	v_mov_b32_e32 v55, v56
	v_lshl_add_u64 v[54:55], v[54:55], 0, s[52:53]
	v_lshl_add_u64 v[54:55], v[54:55], 0, s[24:25]
	v_lshl_add_u64 v[54:55], v[54:55], 0, v[174:175]
	global_store_dwordx4 v[54:55], v[50:53], off
	s_nop 1
	v_mul_f32_e32 v188, v42, v164
	v_mul_f32_e32 v204, v46, v164
	v_mul_f32_e32 v189, v43, v164
	v_mul_f32_e32 v205, v47, v164
	v_mul_f32_e32 v190, v44, v164
	v_mul_f32_e32 v206, v48, v164
	v_mul_f32_e32 v191, v45, v164
	v_mul_f32_e32 v207, v49, v164
	v_mul_f32_e32 v192, v34, v164
	v_mul_f32_e32 v208, v38, v164
	v_mul_f32_e32 v193, v35, v164
	v_mul_f32_e32 v209, v39, v164
	v_mul_f32_e32 v194, v36, v164
	v_mul_f32_e32 v210, v40, v164
	v_mul_f32_e32 v195, v37, v164
	v_mul_f32_e32 v211, v41, v164
	v_mul_f32_e32 v212, 0xbfb8aa3b, v188
	v_mul_f32_e32 v213, 0xbfb8aa3b, v189
	v_mul_f32_e32 v214, 0xbfb8aa3b, v190
	v_mul_f32_e32 v215, 0xbfb8aa3b, v191
	v_mul_f32_e32 v216, 0xbfb8aa3b, v192
	v_mul_f32_e32 v217, 0xbfb8aa3b, v193
	v_mul_f32_e32 v218, 0xbfb8aa3b, v194
	v_mul_f32_e32 v219, 0xbfb8aa3b, v195
	v_exp_f32_e32 v212, v212
	v_exp_f32_e32 v213, v213
	v_exp_f32_e32 v214, v214
	v_exp_f32_e32 v215, v215
	v_exp_f32_e32 v216, v216
	v_exp_f32_e32 v217, v217
	v_exp_f32_e32 v218, v218
	v_exp_f32_e32 v219, v219
	v_add_f32_e32 v212, 1.0, v212
	v_add_f32_e32 v213, 1.0, v213
	v_add_f32_e32 v214, 1.0, v214
	v_add_f32_e32 v215, 1.0, v215
	v_add_f32_e32 v216, 1.0, v216
	v_add_f32_e32 v217, 1.0, v217
	v_add_f32_e32 v218, 1.0, v218
	v_add_f32_e32 v219, 1.0, v219
	v_rcp_f32_e32 v212, v212
	v_rcp_f32_e32 v213, v213
	v_rcp_f32_e32 v214, v214
	v_rcp_f32_e32 v215, v215
	v_rcp_f32_e32 v216, v216
	v_rcp_f32_e32 v217, v217
	v_rcp_f32_e32 v218, v218
	v_rcp_f32_e32 v219, v219
	v_mul_f32_e32 v212, v188, v212
	v_mul_f32_e32 v213, v189, v213
	v_mul_f32_e32 v214, v190, v214
	v_mul_f32_e32 v215, v191, v215
	v_mul_f32_e32 v216, v192, v216
	v_mul_f32_e32 v217, v193, v217
	v_mul_f32_e32 v218, v194, v218
	v_mul_f32_e32 v219, v195, v219
	v_mul_f32_e32 v46, v204, v212
	v_mul_f32_e32 v47, v205, v213
	v_mul_f32_e32 v48, v206, v214
	v_mul_f32_e32 v44, v207, v215
	v_mul_f32_e32 v38, v208, v216
	v_mul_f32_e32 v39, v209, v217
	v_mul_f32_e32 v40, v210, v218
	v_mul_f32_e32 v37, v211, v219
	v_cvt_pk_bf16_f32 v34, v46, v47
	v_cvt_pk_bf16_f32 v35, v48, v44
	v_cvt_pk_bf16_f32 v36, v38, v39
	v_mad_u64_u32 v[38:39], s[54:55], v156, s63, v[114:115]
	v_cvt_pk_bf16_f32 v37, v40, v37
	v_mov_b32_e32 v40, v39
	v_mad_u64_u32 v[40:41], s[54:55], v157, s63, v[40:41]
	v_mov_b32_e32 v39, v40
	v_lshl_add_u64 v[38:39], v[38:39], 0, s[52:53]
	v_lshl_add_u64 v[38:39], v[38:39], 0, s[24:25]
	v_lshl_add_u64 v[38:39], v[38:39], 0, v[174:175]
	global_store_dwordx4 v[38:39], v[34:37], off
	s_nop 1
	v_mul_f32_e32 v188, v26, v160
	v_mul_f32_e32 v204, v30, v160
	v_mul_f32_e32 v189, v27, v160
	v_mul_f32_e32 v205, v31, v160
	v_mul_f32_e32 v190, v28, v160
	v_mul_f32_e32 v206, v32, v160
	v_mul_f32_e32 v191, v29, v160
	v_mul_f32_e32 v207, v33, v160
	v_mul_f32_e32 v192, v18, v160
	v_mul_f32_e32 v208, v22, v160
	v_mul_f32_e32 v193, v19, v160
	v_mul_f32_e32 v209, v23, v160
	v_mul_f32_e32 v194, v20, v160
	v_mul_f32_e32 v210, v24, v160
	v_mul_f32_e32 v195, v21, v160
	v_mul_f32_e32 v211, v25, v160
	v_mul_f32_e32 v212, 0xbfb8aa3b, v188
	v_mul_f32_e32 v213, 0xbfb8aa3b, v189
	v_mul_f32_e32 v214, 0xbfb8aa3b, v190
; __device__ __forceinline__ unsigned cvt_pk_bf16(float lo, float hi) { unsigned r; asm volatile("v_cvt_pk_bf16_f32 %0, %1, %2" : "=v"(r) : "v"(lo), "v"(hi)); return r; }
; #define PG8_BAR __builtin_amdgcn_s_barrier()
; template <class Epi, class Sched, bool ALIGN_EPI = false, bool SP2 = false, bool F16 = false>
; __device__ __forceinline__ void gemm_phase(PG8_LAS unsigned char* lds, const Gemm g, const Sched& S, const Epi& E) {
;     ...
;         if constexpr (ALIGN_EPI) { if (wr == 0) PG8_BAR; }
;         if constexpr (!Epi::AFTER_DRAIN) { E(acc, cur, wr, wc, fr, fq); S.done(cur); }
;         if (!has_next) break;
; #pragma unroll
;         for (int a = 0; a < 2; ++a)
; #pragma unroll
;             for (int b = 0; b < 2; ++b)
; #pragma unroll
;                 for (int m = 0; m < 4; ++m)
; #pragma unroll
;                     for (int n = 0; n < 2; ++n) acc[a][b][m][n] = (f32x4){0.f, 0.f, 0.f, 0.f};
;         cur = nxt; cA = nA; cB = nB; ++ui;
;         if constexpr (ALIGN_EPI) { if (wr == 1) PG8_BAR; }
;     __device__ __forceinline__ void operator()(const f32x4 (&acc)[2][2][4][2], const Unit& u, int wr, int wc, int fr, int fq) const {
;     ...
; #pragma unroll
;         for (int ai = 0; ai < 2; ++ai)
; #pragma unroll
;             for (int m = 0; m < 4; ++m) {
;                 const int row = row0 + ai * HALF + m * 16;
;                 const float rs = rsa[ai][m];
;                 float h[8];
; #pragma unroll
;                 for (int n = 0; n < 2; ++n)
; #pragma unroll
;                     for (int e = 0; e < 4; ++e) {
;                         const float g = acc[ai][0][m][n][e] * rs, uu = acc[ai][1][m][n][e] * rs;
;                         const float sg = __builtin_amdgcn_rcpf(1.f + __builtin_amdgcn_exp2f(g * -1.4426950408889634f));
;                         h[n * 4 + e] = g * sg * uu;
;                     }
;                 u32x4 w; w.x = cvt_pk_bf16(h[0], h[1]); w.y = cvt_pk_bf16(h[2], h[3]); w.z = cvt_pk_bf16(h[4], h[5]); w.w = cvt_pk_bf16(h[6], h[7]);
;                 *(u32x4*)(H + (size_t)row * ldc + u.pn * HALF + wc * 32 + 8 * fq) = w;
	v_mul_f32_e32 v215, 0xbfb8aa3b, v191
	v_mul_f32_e32 v216, 0xbfb8aa3b, v192
	v_mul_f32_e32 v217, 0xbfb8aa3b, v193
	v_mul_f32_e32 v218, 0xbfb8aa3b, v194
	v_mul_f32_e32 v219, 0xbfb8aa3b, v195
	v_exp_f32_e32 v212, v212
	v_exp_f32_e32 v213, v213
	v_exp_f32_e32 v214, v214
	v_exp_f32_e32 v215, v215
	v_exp_f32_e32 v216, v216
	v_exp_f32_e32 v217, v217
	v_exp_f32_e32 v218, v218
	v_exp_f32_e32 v219, v219
	v_add_f32_e32 v212, 1.0, v212
	v_add_f32_e32 v213, 1.0, v213
	v_add_f32_e32 v214, 1.0, v214
	v_add_f32_e32 v215, 1.0, v215
	v_add_f32_e32 v216, 1.0, v216
	v_add_f32_e32 v217, 1.0, v217
	v_add_f32_e32 v218, 1.0, v218
	v_add_f32_e32 v219, 1.0, v219
	v_rcp_f32_e32 v212, v212
	v_rcp_f32_e32 v213, v213
	v_rcp_f32_e32 v214, v214
	v_rcp_f32_e32 v215, v215
	v_rcp_f32_e32 v216, v216
	v_rcp_f32_e32 v217, v217
	v_rcp_f32_e32 v218, v218
	v_rcp_f32_e32 v219, v219
	v_mul_f32_e32 v212, v188, v212
	v_mul_f32_e32 v213, v189, v213
	v_mul_f32_e32 v214, v190, v214
	v_mul_f32_e32 v215, v191, v215
	v_mul_f32_e32 v216, v192, v216
	v_mul_f32_e32 v217, v193, v217
	v_mul_f32_e32 v218, v194, v218
	v_mul_f32_e32 v219, v195, v219
	v_mul_f32_e32 v30, v204, v212
	v_mul_f32_e32 v31, v205, v213
	v_mul_f32_e32 v32, v206, v214
	v_mul_f32_e32 v28, v207, v215
	v_mul_f32_e32 v22, v208, v216
	v_mul_f32_e32 v23, v209, v217
	v_mul_f32_e32 v24, v210, v218
	v_mul_f32_e32 v21, v211, v219
	v_cvt_pk_bf16_f32 v18, v30, v31
	v_cvt_pk_bf16_f32 v19, v32, v28
	v_cvt_pk_bf16_f32 v20, v22, v23
	v_mad_u64_u32 v[22:23], s[54:55], v154, s63, v[114:115]
	v_cvt_pk_bf16_f32 v21, v24, v21
	v_mov_b32_e32 v24, v23
	v_mad_u64_u32 v[24:25], s[54:55], v155, s63, v[24:25]
	v_mov_b32_e32 v23, v24
	v_lshl_add_u64 v[22:23], v[22:23], 0, s[52:53]
	v_lshl_add_u64 v[22:23], v[22:23], 0, s[24:25]
	v_lshl_add_u64 v[22:23], v[22:23], 0, v[174:175]
	global_store_dwordx4 v[22:23], v[18:21], off
	s_nop 1
	v_mul_f32_e32 v188, v10, v130
	v_mul_f32_e32 v204, v14, v130
	v_mul_f32_e32 v189, v11, v130
	v_mul_f32_e32 v205, v15, v130
	v_mul_f32_e32 v190, v12, v130
	v_mul_f32_e32 v206, v16, v130
	v_mul_f32_e32 v191, v13, v130
	v_mul_f32_e32 v207, v17, v130
	v_mul_f32_e32 v192, v6, v130
	v_mul_f32_e32 v208, v2, v130
	v_mul_f32_e32 v193, v7, v130
	v_mul_f32_e32 v209, v3, v130
	v_mul_f32_e32 v194, v8, v130
	v_mul_f32_e32 v210, v4, v130
	v_mul_f32_e32 v195, v9, v130
	v_mul_f32_e32 v211, v5, v130
	v_mul_f32_e32 v212, 0xbfb8aa3b, v188
	v_mul_f32_e32 v213, 0xbfb8aa3b, v189
	v_mul_f32_e32 v214, 0xbfb8aa3b, v190
	v_mul_f32_e32 v215, 0xbfb8aa3b, v191
	v_mul_f32_e32 v216, 0xbfb8aa3b, v192
	v_mul_f32_e32 v217, 0xbfb8aa3b, v193
	v_mul_f32_e32 v218, 0xbfb8aa3b, v194
	v_mul_f32_e32 v219, 0xbfb8aa3b, v195
	v_exp_f32_e32 v212, v212
	v_exp_f32_e32 v213, v213
	v_exp_f32_e32 v214, v214
	v_exp_f32_e32 v215, v215
	v_exp_f32_e32 v216, v216
	v_exp_f32_e32 v217, v217
	v_exp_f32_e32 v218, v218
	v_exp_f32_e32 v219, v219
	v_add_f32_e32 v212, 1.0, v212
	v_add_f32_e32 v213, 1.0, v213
	v_add_f32_e32 v214, 1.0, v214
	v_add_f32_e32 v215, 1.0, v215
	v_add_f32_e32 v216, 1.0, v216
	v_add_f32_e32 v217, 1.0, v217
	v_add_f32_e32 v218, 1.0, v218
	v_add_f32_e32 v219, 1.0, v219
	v_rcp_f32_e32 v212, v212
	v_rcp_f32_e32 v213, v213
	v_rcp_f32_e32 v214, v214
	v_rcp_f32_e32 v215, v215
	v_rcp_f32_e32 v216, v216
	v_rcp_f32_e32 v217, v217
	v_rcp_f32_e32 v218, v218
	v_rcp_f32_e32 v219, v219
	v_mul_f32_e32 v212, v188, v212
	v_mul_f32_e32 v213, v189, v213
	v_mul_f32_e32 v214, v190, v214
	v_mul_f32_e32 v215, v191, v215
	v_mul_f32_e32 v216, v192, v216
	v_mul_f32_e32 v217, v193, v217
	v_mul_f32_e32 v218, v194, v218
	v_mul_f32_e32 v219, v195, v219
	v_mul_f32_e32 v14, v204, v212
	v_mul_f32_e32 v15, v205, v213
	v_mul_f32_e32 v16, v206, v214
	v_mul_f32_e32 v12, v207, v215
	v_mul_f32_e32 v10, v208, v216
	v_mul_f32_e32 v6, v209, v217
	v_mul_f32_e32 v7, v210, v218
	v_mul_f32_e32 v5, v211, v219
	v_cvt_pk_bf16_f32 v2, v14, v15
	v_cvt_pk_bf16_f32 v3, v16, v12
	v_cvt_pk_bf16_f32 v4, v10, v6
	v_cvt_pk_bf16_f32 v5, v7, v5
	v_mad_u64_u32 v[6:7], s[54:55], v152, s63, v[114:115]
	v_mov_b32_e32 v8, v7
	v_mad_u64_u32 v[8:9], s[54:55], v153, s63, v[8:9]
	v_mov_b32_e32 v7, v8
	v_lshl_add_u64 v[6:7], v[6:7], 0, s[52:53]
	v_lshl_add_u64 v[6:7], v[6:7], 0, s[24:25]
	v_lshl_add_u64 v[6:7], v[6:7], 0, v[174:175]
	s_mov_b64 s[52:53], -1
	global_store_dwordx4 v[6:7], v[2:5], off
	s_cbranch_vccnz .LBB0_298
	s_andn2_b64 vcc, exec, s[16:17]
	s_cbranch_vccnz .LBB0_297
	s_barrier
	s_branch .LBB0_297
